# all GEMM K-loop heads aligned to 64 bytes (.p2align 6, s_nop padding executed once per tile) - code placement experiment
# baseline (speedup 1.0000x reference)
; template <class Epi>
; __device__ __forceinline__ void gemm_phase(LAS unsigned char* lds, const Gemm g, const StaticOrder& S, const Epi& E) {
;     ...
;     for (;;) {
;         const bool has_next = S.next(ui + 1, nxt);
;         const char* nA = has_next ? (const char*)g.A + (size_t)nxt.pm * tstepA : cA; const char* nB = has_next ? (const char*)g.Bt + (size_t)nxt.pn * tstepB : cB;
;         for (int t = 0; t < nt; t += 2) {
;             const bool last = (t == nt - 2);
;             const char* a1 = cA + (size_t)(t + 1) * kstep;
;             const char* a2 = last ? nA : cA + (size_t)(t + 2) * kstep; const char* b2 = last ? nB : cB + (size_t)(t + 2) * kstep;
;             const char* a3 = a2 + kstep; const char* b3 = b2 + kstep;
.LBB0_128:
	s_andn2_b64 vcc, exec, s[4:5]
	s_mov_b32 s89, s81
	s_mov_b32 s92, s88
	s_mov_b64 s[6:7], s[20:21]
	s_mov_b64 s[22:23], s[0:1]
	s_cbranch_vccz .LBB0_121
	.p2align	6

; template <class Epi>
; __device__ __forceinline__ void gemm_phase(LAS unsigned char* lds, const Gemm g, const StaticOrder& S, const Epi& E) {
;     ...
;         for (int t = 0; t < nt; t += 2) {
;             const bool last = (t == nt - 2);
;             const char* a1 = cA + (size_t)(t + 1) * kstep;
;             const char* a2 = last ? nA : cA + (size_t)(t + 2) * kstep; const char* b2 = last ? nB : cB + (size_t)(t + 2) * kstep;
;             const char* a3 = a2 + kstep; const char* b3 = b2 + kstep;
;     ...
; #pragma unroll
;         for (int a = 0; a < 2; ++a)
; #pragma unroll
;             for (int b = 0; b < 2; ++b)
; #pragma unroll
;                 for (int m = 0; m < 4; ++m)
; #pragma unroll
;                     for (int n = 0; n < 2; ++n) acc[a][b][m][n] = (f32x4){0.f, 0.f, 0.f, 0.f};
;         cur = nxt; cA = nA; cB = nB; ++ui;
.LBB0_139:
	s_add_u32 s93, s6, 0x100
	s_addc_u32 s94, s7, 0
	v_readlane_b32 s36, v254, 43
	s_add_u32 s6, s22, 0x80
	v_mov_b32_e32 v0, 0
	v_readlane_b32 s44, v254, 51
	v_readlane_b32 s45, v254, 52
	s_addc_u32 s7, s23, 0
	s_mov_b32 s22, 0
	v_mov_b32_e32 v1, v0
	v_mov_b32_e32 v2, v0
	v_mov_b32_e32 v3, v0
	v_mov_b32_e32 v4, v0
	v_mov_b32_e32 v5, v0
	v_mov_b32_e32 v6, v0
	v_mov_b32_e32 v7, v0
	v_mov_b32_e32 v16, v0
	v_mov_b32_e32 v17, v0
	v_mov_b32_e32 v18, v0
	v_mov_b32_e32 v19, v0
	v_mov_b32_e32 v20, v0
	v_mov_b32_e32 v21, v0
	v_mov_b32_e32 v22, v0
	v_mov_b32_e32 v23, v0
	v_mov_b32_e32 v34, v0
	v_mov_b32_e32 v35, v0
	v_mov_b32_e32 v36, v0
	v_mov_b32_e32 v37, v0
	v_mov_b32_e32 v38, v0
	v_mov_b32_e32 v39, v0
	v_mov_b32_e32 v40, v0
	v_mov_b32_e32 v41, v0
	v_mov_b32_e32 v50, v0
	v_mov_b32_e32 v51, v0
	v_mov_b32_e32 v52, v0
	v_mov_b32_e32 v53, v0
	v_mov_b32_e32 v54, v0
	v_mov_b32_e32 v55, v0
	v_mov_b32_e32 v56, v0
	v_mov_b32_e32 v57, v0
	v_mov_b32_e32 v8, v0
	v_mov_b32_e32 v9, v0
	v_mov_b32_e32 v10, v0
	v_mov_b32_e32 v11, v0
	v_mov_b32_e32 v12, v0
	v_mov_b32_e32 v13, v0
	v_mov_b32_e32 v14, v0
	v_mov_b32_e32 v15, v0
	v_mov_b32_e32 v24, v0
	v_mov_b32_e32 v25, v0
	v_mov_b32_e32 v26, v0
	v_mov_b32_e32 v27, v0
	v_mov_b32_e32 v28, v0
	v_mov_b32_e32 v29, v0
	v_mov_b32_e32 v30, v0
	v_mov_b32_e32 v31, v0
	v_mov_b32_e32 v42, v0
	v_mov_b32_e32 v43, v0
	v_mov_b32_e32 v44, v0
	v_mov_b32_e32 v45, v0
	v_mov_b32_e32 v46, v0
	v_mov_b32_e32 v47, v0
	v_mov_b32_e32 v48, v0
	v_mov_b32_e32 v49, v0
	v_mov_b32_e32 v58, v0
	v_mov_b32_e32 v59, v0
	v_mov_b32_e32 v60, v0
	v_mov_b32_e32 v61, v0
	v_mov_b32_e32 v62, v0
	v_mov_b32_e32 v63, v0
	v_mov_b32_e32 v64, v0
	v_mov_b32_e32 v65, v0
	v_mov_b32_e32 v66, v0
	v_mov_b32_e32 v67, v0
	v_mov_b32_e32 v68, v0
	v_mov_b32_e32 v69, v0
	v_mov_b32_e32 v70, v0
	v_mov_b32_e32 v71, v0
	v_mov_b32_e32 v72, v0
	v_mov_b32_e32 v73, v0
	v_mov_b32_e32 v82, v0
	v_mov_b32_e32 v83, v0
	v_mov_b32_e32 v84, v0
	v_mov_b32_e32 v85, v0
	v_mov_b32_e32 v86, v0
	v_mov_b32_e32 v87, v0
	v_mov_b32_e32 v88, v0
	v_mov_b32_e32 v89, v0
	v_mov_b32_e32 v98, v0
	v_mov_b32_e32 v99, v0
	v_mov_b32_e32 v100, v0
	v_mov_b32_e32 v101, v0
	v_mov_b32_e32 v102, v0
	v_mov_b32_e32 v103, v0
	v_mov_b32_e32 v104, v0
	v_mov_b32_e32 v105, v0
	v_mov_b32_e32 v114, v0
	v_mov_b32_e32 v115, v0
	v_mov_b32_e32 v116, v0
	v_mov_b32_e32 v117, v0
	v_mov_b32_e32 v118, v0
	v_mov_b32_e32 v119, v0
	v_mov_b32_e32 v120, v0
	v_mov_b32_e32 v121, v0
	v_mov_b32_e32 v74, v0
	v_mov_b32_e32 v75, v0
	v_mov_b32_e32 v76, v0
	v_mov_b32_e32 v77, v0
	v_mov_b32_e32 v78, v0
	v_mov_b32_e32 v79, v0
	v_mov_b32_e32 v80, v0
	v_mov_b32_e32 v81, v0
	v_mov_b32_e32 v90, v0
	v_mov_b32_e32 v91, v0
	v_mov_b32_e32 v92, v0
	v_mov_b32_e32 v93, v0
	v_mov_b32_e32 v94, v0
	v_mov_b32_e32 v95, v0
	v_mov_b32_e32 v96, v0
	v_mov_b32_e32 v97, v0
	v_mov_b32_e32 v106, v0
	v_mov_b32_e32 v107, v0
	v_mov_b32_e32 v108, v0
	v_mov_b32_e32 v109, v0
	v_mov_b32_e32 v110, v0
	v_mov_b32_e32 v111, v0
	v_mov_b32_e32 v112, v0
	v_mov_b32_e32 v113, v0
	v_mov_b32_e32 v122, v0
	v_mov_b32_e32 v123, v0
	v_mov_b32_e32 v124, v0
	v_mov_b32_e32 v125, v0
	v_mov_b32_e32 v126, v0
	v_mov_b32_e32 v127, v0
	v_mov_b32_e32 v128, v0
	v_mov_b32_e32 v129, v0
	s_mov_b64 s[24:25], s[44:45]
	v_readlane_b32 s37, v254, 44
	v_readlane_b32 s38, v254, 45
	v_readlane_b32 s39, v254, 46
	v_readlane_b32 s40, v254, 47
	v_readlane_b32 s41, v254, 48
	v_readlane_b32 s42, v254, 49
	v_readlane_b32 s43, v254, 50
	v_readlane_b32 s46, v254, 53
	v_readlane_b32 s47, v254, 54
	v_readlane_b32 s48, v254, 55
	v_readlane_b32 s49, v254, 56
	v_readlane_b32 s50, v254, 57
	v_readlane_b32 s51, v254, 58
	.p2align	6

; template <class Epi>
; __device__ __forceinline__ void gemm_phase(LAS unsigned char* lds, const Gemm g, const StaticOrder& S, const Epi& E) {
;     ...
;         const bool has_next = S.next(ui + 1, nxt);
;         const char* nA = has_next ? (const char*)g.A + (size_t)nxt.pm * tstepA : cA; const char* nB = has_next ? (const char*)g.Bt + (size_t)nxt.pn * tstepB : cB;
;         for (int t = 0; t < nt; t += 2) {
;             const bool last = (t == nt - 2);
;             const char* a1 = cA + (size_t)(t + 1) * kstep;
;             const char* a2 = last ? nA : cA + (size_t)(t + 2) * kstep; const char* b2 = last ? nB : cB + (size_t)(t + 2) * kstep;
;             const char* a3 = a2 + kstep; const char* b3 = b2 + kstep;
;     ...
; #pragma unroll
;         for (int a = 0; a < 2; ++a)
; #pragma unroll
;             for (int b = 0; b < 2; ++b)
; #pragma unroll
;                 for (int m = 0; m < 4; ++m)
; #pragma unroll
;                     for (int n = 0; n < 2; ++n) acc[a][b][m][n] = (f32x4){0.f, 0.f, 0.f, 0.f};
;         cur = nxt; cA = nA; cB = nB; ++ui;
.LBB0_213:
	s_ashr_i32 s13, s12, 31
	s_lshl_b64 s[14:15], s[12:13], 19
	s_add_u32 s14, s84, s14
	s_addc_u32 s15, s85, s15
	s_and_b64 s[16:17], s[4:5], exec
	s_cselect_b32 s13, s15, s21
	s_cselect_b32 s70, s14, s20
	s_ashr_i32 s11, s10, 31
	s_lshl_b64 s[16:17], s[10:11], 19
	v_readlane_b32 s22, v255, 5
	v_readlane_b32 s23, v255, 6
	s_add_u32 s16, s22, s16
	s_addc_u32 s17, s23, s17
	s_and_b64 s[22:23], s[4:5], exec
	s_cselect_b32 s11, s17, s19
	s_cselect_b32 s71, s16, s18
	s_add_u32 s72, s18, 0x100
	s_addc_u32 s73, s19, 0
	s_add_u32 s18, s20, 0x40080
	v_mov_b32_e32 v0, 0
	s_addc_u32 s19, s21, 0
	s_mov_b32 s75, -2
	v_mov_b32_e32 v1, v0
	v_mov_b32_e32 v2, v0
	v_mov_b32_e32 v3, v0
	v_mov_b32_e32 v4, v0
	v_mov_b32_e32 v5, v0
	v_mov_b32_e32 v6, v0
	v_mov_b32_e32 v7, v0
	v_mov_b32_e32 v16, v0
	v_mov_b32_e32 v17, v0
	v_mov_b32_e32 v18, v0
	v_mov_b32_e32 v19, v0
	v_mov_b32_e32 v20, v0
	v_mov_b32_e32 v21, v0
	v_mov_b32_e32 v22, v0
	v_mov_b32_e32 v23, v0
	v_mov_b32_e32 v34, v0
	v_mov_b32_e32 v35, v0
	v_mov_b32_e32 v36, v0
	v_mov_b32_e32 v37, v0
	v_mov_b32_e32 v38, v0
	v_mov_b32_e32 v39, v0
	v_mov_b32_e32 v40, v0
	v_mov_b32_e32 v41, v0
	v_mov_b32_e32 v50, v0
	v_mov_b32_e32 v51, v0
	v_mov_b32_e32 v52, v0
	v_mov_b32_e32 v53, v0
	v_mov_b32_e32 v54, v0
	v_mov_b32_e32 v55, v0
	v_mov_b32_e32 v56, v0
	v_mov_b32_e32 v57, v0
	v_mov_b32_e32 v8, v0
	v_mov_b32_e32 v9, v0
	v_mov_b32_e32 v10, v0
	v_mov_b32_e32 v11, v0
	v_mov_b32_e32 v12, v0
	v_mov_b32_e32 v13, v0
	v_mov_b32_e32 v14, v0
	v_mov_b32_e32 v15, v0
	v_mov_b32_e32 v24, v0
	v_mov_b32_e32 v25, v0
	v_mov_b32_e32 v26, v0
	v_mov_b32_e32 v27, v0
	v_mov_b32_e32 v28, v0
	v_mov_b32_e32 v29, v0
	v_mov_b32_e32 v30, v0
	v_mov_b32_e32 v31, v0
	v_mov_b32_e32 v42, v0
	v_mov_b32_e32 v43, v0
	v_mov_b32_e32 v44, v0
	v_mov_b32_e32 v45, v0
	v_mov_b32_e32 v46, v0
	v_mov_b32_e32 v47, v0
	v_mov_b32_e32 v48, v0
	v_mov_b32_e32 v49, v0
	v_mov_b32_e32 v58, v0
	v_mov_b32_e32 v59, v0
	v_mov_b32_e32 v60, v0
	v_mov_b32_e32 v61, v0
	v_mov_b32_e32 v62, v0
	v_mov_b32_e32 v63, v0
	v_mov_b32_e32 v64, v0
	v_mov_b32_e32 v65, v0
	v_mov_b32_e32 v66, v0
	v_mov_b32_e32 v67, v0
	v_mov_b32_e32 v68, v0
	v_mov_b32_e32 v69, v0
	v_mov_b32_e32 v70, v0
	v_mov_b32_e32 v71, v0
	v_mov_b32_e32 v72, v0
	v_mov_b32_e32 v73, v0
	v_mov_b32_e32 v82, v0
	v_mov_b32_e32 v83, v0
	v_mov_b32_e32 v84, v0
	v_mov_b32_e32 v85, v0
	v_mov_b32_e32 v86, v0
	v_mov_b32_e32 v87, v0
	v_mov_b32_e32 v88, v0
	v_mov_b32_e32 v89, v0
	v_mov_b32_e32 v98, v0
	v_mov_b32_e32 v99, v0
	v_mov_b32_e32 v100, v0
	v_mov_b32_e32 v101, v0
	v_mov_b32_e32 v102, v0
	v_mov_b32_e32 v103, v0
	v_mov_b32_e32 v104, v0
	v_mov_b32_e32 v105, v0
	v_mov_b32_e32 v114, v0
	v_mov_b32_e32 v115, v0
	v_mov_b32_e32 v116, v0
	v_mov_b32_e32 v117, v0
	v_mov_b32_e32 v118, v0
	v_mov_b32_e32 v119, v0
	v_mov_b32_e32 v120, v0
	v_mov_b32_e32 v121, v0
	v_mov_b32_e32 v74, v0
	v_mov_b32_e32 v75, v0
	v_mov_b32_e32 v76, v0
	v_mov_b32_e32 v77, v0
	v_mov_b32_e32 v78, v0
	v_mov_b32_e32 v79, v0
	v_mov_b32_e32 v80, v0
	v_mov_b32_e32 v81, v0
	v_mov_b32_e32 v90, v0
	v_mov_b32_e32 v91, v0
	v_mov_b32_e32 v92, v0
	v_mov_b32_e32 v93, v0
	v_mov_b32_e32 v94, v0
	v_mov_b32_e32 v95, v0
	v_mov_b32_e32 v96, v0
	v_mov_b32_e32 v97, v0
	v_mov_b32_e32 v106, v0
	v_mov_b32_e32 v107, v0
	v_mov_b32_e32 v108, v0
	v_mov_b32_e32 v109, v0
	v_mov_b32_e32 v110, v0
	v_mov_b32_e32 v111, v0
	v_mov_b32_e32 v112, v0
	v_mov_b32_e32 v113, v0
	v_mov_b32_e32 v122, v0
	v_mov_b32_e32 v123, v0
	v_mov_b32_e32 v124, v0
	v_mov_b32_e32 v125, v0
	v_mov_b32_e32 v126, v0
	v_mov_b32_e32 v127, v0
	v_mov_b32_e32 v128, v0
	v_mov_b32_e32 v129, v0
	.p2align	6

; template <class Epi>
; __device__ __forceinline__ void gemm_phase(LAS unsigned char* lds, const Gemm g, const StaticOrder& S, const Epi& E) {
;     ...
;         for (int t = 0; t < nt; t += 2) {
;             const bool last = (t == nt - 2);
;             const char* a1 = cA + (size_t)(t + 1) * kstep;
;             const char* a2 = last ? nA : cA + (size_t)(t + 2) * kstep; const char* b2 = last ? nB : cB + (size_t)(t + 2) * kstep;
;             const char* a3 = a2 + kstep; const char* b3 = b2 + kstep;
;     ...
; #pragma unroll
;         for (int a = 0; a < 2; ++a)
; #pragma unroll
;             for (int b = 0; b < 2; ++b)
; #pragma unroll
;                 for (int m = 0; m < 4; ++m)
; #pragma unroll
;                     for (int n = 0; n < 2; ++n) acc[a][b][m][n] = (f32x4){0.f, 0.f, 0.f, 0.f};
;         cur = nxt; cA = nA; cB = nB; ++ui;
.LBB0_563:
	s_add_u32 s30, s26, 0x100
	s_addc_u32 s31, s27, 0
	s_add_u32 s26, s28, 0x80
	v_mov_b32_e32 v0, 0
	s_addc_u32 s27, s29, 0
	s_mov_b32 s28, 0
	v_mov_b32_e32 v1, v0
	v_mov_b32_e32 v2, v0
	v_mov_b32_e32 v3, v0
	v_mov_b32_e32 v4, v0
	v_mov_b32_e32 v5, v0
	v_mov_b32_e32 v6, v0
	v_mov_b32_e32 v7, v0
	v_mov_b32_e32 v16, v0
	v_mov_b32_e32 v17, v0
	v_mov_b32_e32 v18, v0
	v_mov_b32_e32 v19, v0
	v_mov_b32_e32 v20, v0
	v_mov_b32_e32 v21, v0
	v_mov_b32_e32 v22, v0
	v_mov_b32_e32 v23, v0
	v_mov_b32_e32 v34, v0
	v_mov_b32_e32 v35, v0
	v_mov_b32_e32 v36, v0
	v_mov_b32_e32 v37, v0
	v_mov_b32_e32 v38, v0
	v_mov_b32_e32 v39, v0
	v_mov_b32_e32 v40, v0
	v_mov_b32_e32 v41, v0
	v_mov_b32_e32 v50, v0
	v_mov_b32_e32 v51, v0
	v_mov_b32_e32 v52, v0
	v_mov_b32_e32 v53, v0
	v_mov_b32_e32 v54, v0
	v_mov_b32_e32 v55, v0
	v_mov_b32_e32 v56, v0
	v_mov_b32_e32 v57, v0
	v_mov_b32_e32 v8, v0
	v_mov_b32_e32 v9, v0
	v_mov_b32_e32 v10, v0
	v_mov_b32_e32 v11, v0
	v_mov_b32_e32 v12, v0
	v_mov_b32_e32 v13, v0
	v_mov_b32_e32 v14, v0
	v_mov_b32_e32 v15, v0
	v_mov_b32_e32 v24, v0
	v_mov_b32_e32 v25, v0
	v_mov_b32_e32 v26, v0
	v_mov_b32_e32 v27, v0
	v_mov_b32_e32 v28, v0
	v_mov_b32_e32 v29, v0
	v_mov_b32_e32 v30, v0
	v_mov_b32_e32 v31, v0
	v_mov_b32_e32 v42, v0
	v_mov_b32_e32 v43, v0
	v_mov_b32_e32 v44, v0
	v_mov_b32_e32 v45, v0
	v_mov_b32_e32 v46, v0
	v_mov_b32_e32 v47, v0
	v_mov_b32_e32 v48, v0
	v_mov_b32_e32 v49, v0
	v_mov_b32_e32 v58, v0
	v_mov_b32_e32 v59, v0
	v_mov_b32_e32 v60, v0
	v_mov_b32_e32 v61, v0
	v_mov_b32_e32 v62, v0
	v_mov_b32_e32 v63, v0
	v_mov_b32_e32 v64, v0
	v_mov_b32_e32 v65, v0
	v_mov_b32_e32 v66, v0
	v_mov_b32_e32 v67, v0
	v_mov_b32_e32 v68, v0
	v_mov_b32_e32 v69, v0
	v_mov_b32_e32 v70, v0
	v_mov_b32_e32 v71, v0
	v_mov_b32_e32 v72, v0
	v_mov_b32_e32 v73, v0
	v_mov_b32_e32 v82, v0
	v_mov_b32_e32 v83, v0
	v_mov_b32_e32 v84, v0
	v_mov_b32_e32 v85, v0
	v_mov_b32_e32 v86, v0
	v_mov_b32_e32 v87, v0
	v_mov_b32_e32 v88, v0
	v_mov_b32_e32 v89, v0
	v_mov_b32_e32 v98, v0
	v_mov_b32_e32 v99, v0
	v_mov_b32_e32 v100, v0
	v_mov_b32_e32 v101, v0
	v_mov_b32_e32 v102, v0
	v_mov_b32_e32 v103, v0
	v_mov_b32_e32 v104, v0
	v_mov_b32_e32 v105, v0
	v_mov_b32_e32 v114, v0
	v_mov_b32_e32 v115, v0
	v_mov_b32_e32 v116, v0
	v_mov_b32_e32 v117, v0
	v_mov_b32_e32 v118, v0
	v_mov_b32_e32 v119, v0
	v_mov_b32_e32 v120, v0
	v_mov_b32_e32 v121, v0
	v_mov_b32_e32 v74, v0
	v_mov_b32_e32 v75, v0
	v_mov_b32_e32 v76, v0
	v_mov_b32_e32 v77, v0
	v_mov_b32_e32 v78, v0
	v_mov_b32_e32 v79, v0
	v_mov_b32_e32 v80, v0
	v_mov_b32_e32 v81, v0
	v_mov_b32_e32 v90, v0
	v_mov_b32_e32 v91, v0
	v_mov_b32_e32 v92, v0
	v_mov_b32_e32 v93, v0
	v_mov_b32_e32 v94, v0
	v_mov_b32_e32 v95, v0
	v_mov_b32_e32 v96, v0
	v_mov_b32_e32 v97, v0
	v_mov_b32_e32 v106, v0
	v_mov_b32_e32 v107, v0
	v_mov_b32_e32 v108, v0
	v_mov_b32_e32 v109, v0
	v_mov_b32_e32 v110, v0
	v_mov_b32_e32 v111, v0
	v_mov_b32_e32 v112, v0
	v_mov_b32_e32 v113, v0
	v_mov_b32_e32 v122, v0
	v_mov_b32_e32 v123, v0
	v_mov_b32_e32 v124, v0
	v_mov_b32_e32 v125, v0
	v_mov_b32_e32 v126, v0
	v_mov_b32_e32 v127, v0
	v_mov_b32_e32 v128, v0
	v_mov_b32_e32 v129, v0
	.p2align	6

; template <class Epi>
; __device__ __forceinline__ void gemm_phase(LAS unsigned char* lds, const Gemm g, const StaticOrder& S, const Epi& E) {
;     ...
; #pragma unroll
;         for (int a = 0; a < 2; ++a)
; #pragma unroll
;             for (int b = 0; b < 2; ++b)
; #pragma unroll
;                 for (int m = 0; m < 4; ++m)
; #pragma unroll
;                     for (int n = 0; n < 2; ++n) acc[a][b][m][n] = (f32x4){0.f, 0.f, 0.f, 0.f};
;         cur = nxt; cA = nA; cB = nB; ++ui;
.LBB0_630:
	s_add_u32 s28, s22, 0x100
	s_addc_u32 s29, s23, 0
	s_add_u32 s22, s26, 0x80
	v_mov_b32_e32 v0, 0
	s_addc_u32 s23, s27, 0
	s_mov_b32 s26, 0
	v_mov_b32_e32 v1, v0
	v_mov_b32_e32 v2, v0
	v_mov_b32_e32 v3, v0
	v_mov_b32_e32 v4, v0
	v_mov_b32_e32 v5, v0
	v_mov_b32_e32 v6, v0
	v_mov_b32_e32 v7, v0
	v_mov_b32_e32 v16, v0
	v_mov_b32_e32 v17, v0
	v_mov_b32_e32 v18, v0
	v_mov_b32_e32 v19, v0
	v_mov_b32_e32 v20, v0
	v_mov_b32_e32 v21, v0
	v_mov_b32_e32 v22, v0
	v_mov_b32_e32 v23, v0
	v_mov_b32_e32 v34, v0
	v_mov_b32_e32 v35, v0
	v_mov_b32_e32 v36, v0
	v_mov_b32_e32 v37, v0
	v_mov_b32_e32 v38, v0
	v_mov_b32_e32 v39, v0
	v_mov_b32_e32 v40, v0
	v_mov_b32_e32 v41, v0
	v_mov_b32_e32 v50, v0
	v_mov_b32_e32 v51, v0
	v_mov_b32_e32 v52, v0
	v_mov_b32_e32 v53, v0
	v_mov_b32_e32 v54, v0
	v_mov_b32_e32 v55, v0
	v_mov_b32_e32 v56, v0
	v_mov_b32_e32 v57, v0
	v_mov_b32_e32 v8, v0
	v_mov_b32_e32 v9, v0
	v_mov_b32_e32 v10, v0
	v_mov_b32_e32 v11, v0
	v_mov_b32_e32 v12, v0
	v_mov_b32_e32 v13, v0
	v_mov_b32_e32 v14, v0
	v_mov_b32_e32 v15, v0
	v_mov_b32_e32 v24, v0
	v_mov_b32_e32 v25, v0
	v_mov_b32_e32 v26, v0
	v_mov_b32_e32 v27, v0
	v_mov_b32_e32 v28, v0
	v_mov_b32_e32 v29, v0
	v_mov_b32_e32 v30, v0
	v_mov_b32_e32 v31, v0
	v_mov_b32_e32 v42, v0
	v_mov_b32_e32 v43, v0
	v_mov_b32_e32 v44, v0
	v_mov_b32_e32 v45, v0
	v_mov_b32_e32 v46, v0
	v_mov_b32_e32 v47, v0
	v_mov_b32_e32 v48, v0
	v_mov_b32_e32 v49, v0
	v_mov_b32_e32 v58, v0
	v_mov_b32_e32 v59, v0
	v_mov_b32_e32 v60, v0
	v_mov_b32_e32 v61, v0
	v_mov_b32_e32 v62, v0
	v_mov_b32_e32 v63, v0
	v_mov_b32_e32 v64, v0
	v_mov_b32_e32 v65, v0
	v_mov_b32_e32 v66, v0
	v_mov_b32_e32 v67, v0
	v_mov_b32_e32 v68, v0
	v_mov_b32_e32 v69, v0
	v_mov_b32_e32 v70, v0
	v_mov_b32_e32 v71, v0
	v_mov_b32_e32 v72, v0
	v_mov_b32_e32 v73, v0
	v_mov_b32_e32 v82, v0
	v_mov_b32_e32 v83, v0
	v_mov_b32_e32 v84, v0
	v_mov_b32_e32 v85, v0
	v_mov_b32_e32 v86, v0
	v_mov_b32_e32 v87, v0
	v_mov_b32_e32 v88, v0
	v_mov_b32_e32 v89, v0
	v_mov_b32_e32 v98, v0
	v_mov_b32_e32 v99, v0
	v_mov_b32_e32 v100, v0
	v_mov_b32_e32 v101, v0
	v_mov_b32_e32 v102, v0
	v_mov_b32_e32 v103, v0
	v_mov_b32_e32 v104, v0
	v_mov_b32_e32 v105, v0
	v_mov_b32_e32 v114, v0
	v_mov_b32_e32 v115, v0
	v_mov_b32_e32 v116, v0
	v_mov_b32_e32 v117, v0
	v_mov_b32_e32 v118, v0
	v_mov_b32_e32 v119, v0
	v_mov_b32_e32 v120, v0
	v_mov_b32_e32 v121, v0
	v_mov_b32_e32 v74, v0
	v_mov_b32_e32 v75, v0
	v_mov_b32_e32 v76, v0
	v_mov_b32_e32 v77, v0
	v_mov_b32_e32 v78, v0
	v_mov_b32_e32 v79, v0
	v_mov_b32_e32 v80, v0
	v_mov_b32_e32 v81, v0
	v_mov_b32_e32 v90, v0
	v_mov_b32_e32 v91, v0
	v_mov_b32_e32 v92, v0
	v_mov_b32_e32 v93, v0
	v_mov_b32_e32 v94, v0
	v_mov_b32_e32 v95, v0
	v_mov_b32_e32 v96, v0
	v_mov_b32_e32 v97, v0
	v_mov_b32_e32 v106, v0
	v_mov_b32_e32 v107, v0
	v_mov_b32_e32 v108, v0
	v_mov_b32_e32 v109, v0
	v_mov_b32_e32 v110, v0
	v_mov_b32_e32 v111, v0
	v_mov_b32_e32 v112, v0
	v_mov_b32_e32 v113, v0
	v_mov_b32_e32 v122, v0
	v_mov_b32_e32 v123, v0
	v_mov_b32_e32 v124, v0
	v_mov_b32_e32 v125, v0
	v_mov_b32_e32 v126, v0
	v_mov_b32_e32 v127, v0
	v_mov_b32_e32 v128, v0
	v_mov_b32_e32 v129, v0
	.p2align	6

; template <class Epi>
; __device__ __forceinline__ void gemm_phase(LAS unsigned char* lds, const Gemm g, const StaticOrder& S, const Epi& E) {
;     ...
; #pragma unroll
;         for (int a = 0; a < 2; ++a)
; #pragma unroll
;             for (int b = 0; b < 2; ++b)
; #pragma unroll
;                 for (int m = 0; m < 4; ++m)
; #pragma unroll
;                     for (int n = 0; n < 2; ++n) acc[a][b][m][n] = (f32x4){0.f, 0.f, 0.f, 0.f};
;         cur = nxt; cA = nA; cB = nB; ++ui;
.LBB0_698:
	s_add_u32 s75, s20, 0x100
	v_mov_b32_e32 v0, 0
	s_addc_u32 s76, s21, 0
	s_mov_b32 s78, -2
	v_mov_b32_e32 v1, v0
	v_mov_b32_e32 v2, v0
	v_mov_b32_e32 v3, v0
	v_mov_b32_e32 v4, v0
	v_mov_b32_e32 v5, v0
	v_mov_b32_e32 v6, v0
	v_mov_b32_e32 v7, v0
	v_mov_b32_e32 v16, v0
	v_mov_b32_e32 v17, v0
	v_mov_b32_e32 v18, v0
	v_mov_b32_e32 v19, v0
	v_mov_b32_e32 v20, v0
	v_mov_b32_e32 v21, v0
	v_mov_b32_e32 v22, v0
	v_mov_b32_e32 v23, v0
	v_mov_b32_e32 v34, v0
	v_mov_b32_e32 v35, v0
	v_mov_b32_e32 v36, v0
	v_mov_b32_e32 v37, v0
	v_mov_b32_e32 v38, v0
	v_mov_b32_e32 v39, v0
	v_mov_b32_e32 v40, v0
	v_mov_b32_e32 v41, v0
	v_mov_b32_e32 v50, v0
	v_mov_b32_e32 v51, v0
	v_mov_b32_e32 v52, v0
	v_mov_b32_e32 v53, v0
	v_mov_b32_e32 v54, v0
	v_mov_b32_e32 v55, v0
	v_mov_b32_e32 v56, v0
	v_mov_b32_e32 v57, v0
	v_mov_b32_e32 v8, v0
	v_mov_b32_e32 v9, v0
	v_mov_b32_e32 v10, v0
	v_mov_b32_e32 v11, v0
	v_mov_b32_e32 v12, v0
	v_mov_b32_e32 v13, v0
	v_mov_b32_e32 v14, v0
	v_mov_b32_e32 v15, v0
	v_mov_b32_e32 v24, v0
	v_mov_b32_e32 v25, v0
	v_mov_b32_e32 v26, v0
	v_mov_b32_e32 v27, v0
	v_mov_b32_e32 v28, v0
	v_mov_b32_e32 v29, v0
	v_mov_b32_e32 v30, v0
	v_mov_b32_e32 v31, v0
	v_mov_b32_e32 v42, v0
	v_mov_b32_e32 v43, v0
	v_mov_b32_e32 v44, v0
	v_mov_b32_e32 v45, v0
	v_mov_b32_e32 v46, v0
	v_mov_b32_e32 v47, v0
	v_mov_b32_e32 v48, v0
	v_mov_b32_e32 v49, v0
	v_mov_b32_e32 v58, v0
	v_mov_b32_e32 v59, v0
	v_mov_b32_e32 v60, v0
	v_mov_b32_e32 v61, v0
	v_mov_b32_e32 v62, v0
	v_mov_b32_e32 v63, v0
	v_mov_b32_e32 v64, v0
	v_mov_b32_e32 v65, v0
	v_mov_b32_e32 v66, v0
	v_mov_b32_e32 v67, v0
	v_mov_b32_e32 v68, v0
	v_mov_b32_e32 v69, v0
	v_mov_b32_e32 v70, v0
	v_mov_b32_e32 v71, v0
	v_mov_b32_e32 v72, v0
	v_mov_b32_e32 v73, v0
	v_mov_b32_e32 v82, v0
	v_mov_b32_e32 v83, v0
	v_mov_b32_e32 v84, v0
	v_mov_b32_e32 v85, v0
	v_mov_b32_e32 v86, v0
	v_mov_b32_e32 v87, v0
	v_mov_b32_e32 v88, v0
	v_mov_b32_e32 v89, v0
	v_mov_b32_e32 v98, v0
	v_mov_b32_e32 v99, v0
	v_mov_b32_e32 v100, v0
	v_mov_b32_e32 v101, v0
	v_mov_b32_e32 v102, v0
	v_mov_b32_e32 v103, v0
	v_mov_b32_e32 v104, v0
	v_mov_b32_e32 v105, v0
	v_mov_b32_e32 v114, v0
	v_mov_b32_e32 v115, v0
	v_mov_b32_e32 v116, v0
	v_mov_b32_e32 v117, v0
	v_mov_b32_e32 v118, v0
	v_mov_b32_e32 v119, v0
	v_mov_b32_e32 v120, v0
	v_mov_b32_e32 v121, v0
	v_mov_b32_e32 v74, v0
	v_mov_b32_e32 v75, v0
	v_mov_b32_e32 v76, v0
	v_mov_b32_e32 v77, v0
	v_mov_b32_e32 v78, v0
	v_mov_b32_e32 v79, v0
	v_mov_b32_e32 v80, v0
	v_mov_b32_e32 v81, v0
	v_mov_b32_e32 v90, v0
	v_mov_b32_e32 v91, v0
	v_mov_b32_e32 v92, v0
	v_mov_b32_e32 v93, v0
	v_mov_b32_e32 v94, v0
	v_mov_b32_e32 v95, v0
	v_mov_b32_e32 v96, v0
	v_mov_b32_e32 v97, v0
	v_mov_b32_e32 v106, v0
	v_mov_b32_e32 v107, v0
	v_mov_b32_e32 v108, v0
	v_mov_b32_e32 v109, v0
	v_mov_b32_e32 v110, v0
	v_mov_b32_e32 v111, v0
	v_mov_b32_e32 v112, v0
	v_mov_b32_e32 v113, v0
	v_mov_b32_e32 v122, v0
	v_mov_b32_e32 v123, v0
	v_mov_b32_e32 v124, v0
	v_mov_b32_e32 v125, v0
	v_mov_b32_e32 v126, v0
	v_mov_b32_e32 v127, v0
	v_mov_b32_e32 v128, v0
	v_mov_b32_e32 v129, v0
	.p2align	6

; template <class Epi>
; __device__ __forceinline__ void gemm_phase(LAS unsigned char* lds, const Gemm g, const StaticOrder& S, const Epi& E) {
;     ...
;         const bool has_next = S.next(ui + 1, nxt);
;         const char* nA = has_next ? (const char*)g.A + (size_t)nxt.pm * tstepA : cA; const char* nB = has_next ? (const char*)g.Bt + (size_t)nxt.pn * tstepB : cB;
;     ...
; #pragma unroll
;         for (int a = 0; a < 2; ++a)
; #pragma unroll
;             for (int b = 0; b < 2; ++b)
; #pragma unroll
;                 for (int m = 0; m < 4; ++m)
; #pragma unroll
;                     for (int n = 0; n < 2; ++n) acc[a][b][m][n] = (f32x4){0.f, 0.f, 0.f, 0.f};
;         cur = nxt; cA = nA; cB = nB; ++ui;
.LBB0_752:
	s_ashr_i32 s11, s10, 31
	s_lshl_b64 s[12:13], s[10:11], 19
	s_add_u32 s12, s84, s12
	s_addc_u32 s13, s85, s13
	s_and_b64 s[14:15], s[4:5], exec
	s_cselect_b32 s11, s13, s21
	s_cselect_b32 s68, s12, s20
	s_ashr_i32 s9, s8, 31
	s_lshl_b64 s[14:15], s[8:9], 19
	s_add_u32 s14, s24, s14
	s_addc_u32 s15, s26, s15
	s_and_b64 s[22:23], s[4:5], exec
	s_cselect_b32 s9, s15, s19
	s_cselect_b32 s69, s14, s18
	s_add_u32 s70, s18, 0x100
	s_addc_u32 s71, s19, 0
	s_add_u32 s18, s20, 0x40080
	v_mov_b32_e32 v0, 0
	s_addc_u32 s19, s21, 0
	s_mov_b32 s72, -2
	v_mov_b32_e32 v1, v0
	v_mov_b32_e32 v2, v0
	v_mov_b32_e32 v3, v0
	v_mov_b32_e32 v8, v0
	v_mov_b32_e32 v9, v0
	v_mov_b32_e32 v10, v0
	v_mov_b32_e32 v11, v0
	v_mov_b32_e32 v16, v0
	v_mov_b32_e32 v17, v0
	v_mov_b32_e32 v18, v0
	v_mov_b32_e32 v19, v0
	v_mov_b32_e32 v24, v0
	v_mov_b32_e32 v25, v0
	v_mov_b32_e32 v26, v0
	v_mov_b32_e32 v27, v0
	v_mov_b32_e32 v34, v0
	v_mov_b32_e32 v35, v0
	v_mov_b32_e32 v36, v0
	v_mov_b32_e32 v37, v0
	v_mov_b32_e32 v42, v0
	v_mov_b32_e32 v43, v0
	v_mov_b32_e32 v44, v0
	v_mov_b32_e32 v45, v0
	v_mov_b32_e32 v50, v0
	v_mov_b32_e32 v51, v0
	v_mov_b32_e32 v52, v0
	v_mov_b32_e32 v53, v0
	v_mov_b32_e32 v58, v0
	v_mov_b32_e32 v59, v0
	v_mov_b32_e32 v60, v0
	v_mov_b32_e32 v61, v0
	v_mov_b32_e32 v4, v0
	v_mov_b32_e32 v5, v0
	v_mov_b32_e32 v6, v0
	v_mov_b32_e32 v7, v0
	v_mov_b32_e32 v12, v0
	v_mov_b32_e32 v13, v0
	v_mov_b32_e32 v14, v0
	v_mov_b32_e32 v15, v0
	v_mov_b32_e32 v20, v0
	v_mov_b32_e32 v21, v0
	v_mov_b32_e32 v22, v0
	v_mov_b32_e32 v23, v0
	v_mov_b32_e32 v28, v0
	v_mov_b32_e32 v29, v0
	v_mov_b32_e32 v30, v0
	v_mov_b32_e32 v31, v0
	v_mov_b32_e32 v38, v0
	v_mov_b32_e32 v39, v0
	v_mov_b32_e32 v40, v0
	v_mov_b32_e32 v41, v0
	v_mov_b32_e32 v46, v0
	v_mov_b32_e32 v47, v0
	v_mov_b32_e32 v48, v0
	v_mov_b32_e32 v49, v0
	v_mov_b32_e32 v54, v0
	v_mov_b32_e32 v55, v0
	v_mov_b32_e32 v56, v0
	v_mov_b32_e32 v57, v0
	v_mov_b32_e32 v62, v0
	v_mov_b32_e32 v63, v0
	v_mov_b32_e32 v64, v0
	v_mov_b32_e32 v65, v0
	v_mov_b32_e32 v66, v0
	v_mov_b32_e32 v67, v0
	v_mov_b32_e32 v68, v0
	v_mov_b32_e32 v69, v0
	v_mov_b32_e32 v74, v0
	v_mov_b32_e32 v75, v0
	v_mov_b32_e32 v76, v0
	v_mov_b32_e32 v77, v0
	v_mov_b32_e32 v82, v0
	v_mov_b32_e32 v83, v0
	v_mov_b32_e32 v84, v0
	v_mov_b32_e32 v85, v0
	v_mov_b32_e32 v90, v0
	v_mov_b32_e32 v91, v0
	v_mov_b32_e32 v92, v0
	v_mov_b32_e32 v93, v0
	v_mov_b32_e32 v98, v0
	v_mov_b32_e32 v99, v0
	v_mov_b32_e32 v100, v0
	v_mov_b32_e32 v101, v0
	v_mov_b32_e32 v106, v0
	v_mov_b32_e32 v107, v0
	v_mov_b32_e32 v108, v0
	v_mov_b32_e32 v109, v0
	v_mov_b32_e32 v114, v0
	v_mov_b32_e32 v115, v0
	v_mov_b32_e32 v116, v0
	v_mov_b32_e32 v117, v0
	v_mov_b32_e32 v122, v0
	v_mov_b32_e32 v123, v0
	v_mov_b32_e32 v124, v0
	v_mov_b32_e32 v125, v0
	v_mov_b32_e32 v70, v0
	v_mov_b32_e32 v71, v0
	v_mov_b32_e32 v72, v0
	v_mov_b32_e32 v73, v0
	v_mov_b32_e32 v78, v0
	v_mov_b32_e32 v79, v0
	v_mov_b32_e32 v80, v0
	v_mov_b32_e32 v81, v0
	v_mov_b32_e32 v86, v0
	v_mov_b32_e32 v87, v0
	v_mov_b32_e32 v88, v0
	v_mov_b32_e32 v89, v0
	v_mov_b32_e32 v94, v0
	v_mov_b32_e32 v95, v0
	v_mov_b32_e32 v96, v0
	v_mov_b32_e32 v97, v0
	v_mov_b32_e32 v102, v0
	v_mov_b32_e32 v103, v0
	v_mov_b32_e32 v104, v0
	v_mov_b32_e32 v105, v0
	v_mov_b32_e32 v110, v0
	v_mov_b32_e32 v111, v0
	v_mov_b32_e32 v112, v0
	v_mov_b32_e32 v113, v0
	v_mov_b32_e32 v118, v0
	v_mov_b32_e32 v119, v0
	v_mov_b32_e32 v120, v0
	v_mov_b32_e32 v121, v0
	v_mov_b32_e32 v126, v0
	v_mov_b32_e32 v127, v0
	v_mov_b32_e32 v128, v0
	v_mov_b32_e32 v129, v0
	.p2align	6

; template <class Epi>
; __device__ __forceinline__ void gemm_phase(LAS unsigned char* lds, const Gemm g, const StaticOrder& S, const Epi& E) {
;     ...
;         const bool has_next = S.next(ui + 1, nxt);
;         const char* nA = has_next ? (const char*)g.A + (size_t)nxt.pm * tstepA : cA; const char* nB = has_next ? (const char*)g.Bt + (size_t)nxt.pn * tstepB : cB;
;     ...
; #pragma unroll
;         for (int a = 0; a < 2; ++a)
; #pragma unroll
;             for (int b = 0; b < 2; ++b)
; #pragma unroll
;                 for (int m = 0; m < 4; ++m)
; #pragma unroll
;                     for (int n = 0; n < 2; ++n) acc[a][b][m][n] = (f32x4){0.f, 0.f, 0.f, 0.f};
;         cur = nxt; cA = nA; cB = nB; ++ui;
.LBB0_915:
	s_ashr_i32 s19, s18, 31
	s_lshl_b64 s[20:21], s[18:19], 19
	s_add_u32 s20, s84, s20
	s_addc_u32 s21, s85, s21
	s_and_b64 s[22:23], s[6:7], exec
	s_cselect_b32 s19, s21, s31
	s_cselect_b32 s27, s20, s30
	s_ashr_i32 s17, s16, 31
	s_lshl_b64 s[22:23], s[16:17], 19
	s_add_u32 s22, s35, s22
	s_addc_u32 s23, s3, s23
	s_and_b64 s[68:69], s[6:7], exec
	s_cselect_b32 s17, s23, s29
	s_cselect_b32 s94, s22, s28
	s_add_u32 s95, s28, 0x100
	s_addc_u32 s96, s29, 0
	s_add_u32 s28, s30, 0x40080
	v_mov_b32_e32 v0, 0
	s_addc_u32 s29, s31, 0
	s_mov_b32 s97, -2
	v_mov_b32_e32 v1, v0
	v_mov_b32_e32 v2, v0
	v_mov_b32_e32 v3, v0
	v_mov_b32_e32 v4, v0
	v_mov_b32_e32 v5, v0
	v_mov_b32_e32 v6, v0
	v_mov_b32_e32 v7, v0
	v_mov_b32_e32 v16, v0
	v_mov_b32_e32 v17, v0
	v_mov_b32_e32 v18, v0
	v_mov_b32_e32 v19, v0
	v_mov_b32_e32 v20, v0
	v_mov_b32_e32 v21, v0
	v_mov_b32_e32 v22, v0
	v_mov_b32_e32 v23, v0
	v_mov_b32_e32 v34, v0
	v_mov_b32_e32 v35, v0
	v_mov_b32_e32 v36, v0
	v_mov_b32_e32 v37, v0
	v_mov_b32_e32 v38, v0
	v_mov_b32_e32 v39, v0
	v_mov_b32_e32 v40, v0
	v_mov_b32_e32 v41, v0
	v_mov_b32_e32 v50, v0
	v_mov_b32_e32 v51, v0
	v_mov_b32_e32 v52, v0
	v_mov_b32_e32 v53, v0
	v_mov_b32_e32 v54, v0
	v_mov_b32_e32 v55, v0
	v_mov_b32_e32 v56, v0
	v_mov_b32_e32 v57, v0
	v_mov_b32_e32 v8, v0
	v_mov_b32_e32 v9, v0
	v_mov_b32_e32 v10, v0
	v_mov_b32_e32 v11, v0
	v_mov_b32_e32 v12, v0
	v_mov_b32_e32 v13, v0
	v_mov_b32_e32 v14, v0
	v_mov_b32_e32 v15, v0
	v_mov_b32_e32 v24, v0
	v_mov_b32_e32 v25, v0
	v_mov_b32_e32 v26, v0
	v_mov_b32_e32 v27, v0
	v_mov_b32_e32 v28, v0
	v_mov_b32_e32 v29, v0
	v_mov_b32_e32 v30, v0
	v_mov_b32_e32 v31, v0
	v_mov_b32_e32 v42, v0
	v_mov_b32_e32 v43, v0
	v_mov_b32_e32 v44, v0
	v_mov_b32_e32 v45, v0
	v_mov_b32_e32 v46, v0
	v_mov_b32_e32 v47, v0
	v_mov_b32_e32 v48, v0
	v_mov_b32_e32 v49, v0
	v_mov_b32_e32 v58, v0
	v_mov_b32_e32 v59, v0
	v_mov_b32_e32 v60, v0
	v_mov_b32_e32 v61, v0
	v_mov_b32_e32 v62, v0
	v_mov_b32_e32 v63, v0
	v_mov_b32_e32 v64, v0
	v_mov_b32_e32 v65, v0
	v_mov_b32_e32 v66, v0
	v_mov_b32_e32 v67, v0
	v_mov_b32_e32 v68, v0
	v_mov_b32_e32 v69, v0
	v_mov_b32_e32 v70, v0
	v_mov_b32_e32 v71, v0
	v_mov_b32_e32 v72, v0
	v_mov_b32_e32 v73, v0
	v_mov_b32_e32 v82, v0
	v_mov_b32_e32 v83, v0
	v_mov_b32_e32 v84, v0
	v_mov_b32_e32 v85, v0
	v_mov_b32_e32 v86, v0
	v_mov_b32_e32 v87, v0
	v_mov_b32_e32 v88, v0
	v_mov_b32_e32 v89, v0
	v_mov_b32_e32 v98, v0
	v_mov_b32_e32 v99, v0
	v_mov_b32_e32 v100, v0
	v_mov_b32_e32 v101, v0
	v_mov_b32_e32 v102, v0
	v_mov_b32_e32 v103, v0
	v_mov_b32_e32 v104, v0
	v_mov_b32_e32 v105, v0
	v_mov_b32_e32 v114, v0
	v_mov_b32_e32 v115, v0
	v_mov_b32_e32 v116, v0
	v_mov_b32_e32 v117, v0
	v_mov_b32_e32 v118, v0
	v_mov_b32_e32 v119, v0
	v_mov_b32_e32 v120, v0
	v_mov_b32_e32 v121, v0
	v_mov_b32_e32 v74, v0
	v_mov_b32_e32 v75, v0
	v_mov_b32_e32 v76, v0
	v_mov_b32_e32 v77, v0
	v_mov_b32_e32 v78, v0
	v_mov_b32_e32 v79, v0
	v_mov_b32_e32 v80, v0
	v_mov_b32_e32 v81, v0
	v_mov_b32_e32 v90, v0
	v_mov_b32_e32 v91, v0
	v_mov_b32_e32 v92, v0
	v_mov_b32_e32 v93, v0
	v_mov_b32_e32 v94, v0
	v_mov_b32_e32 v95, v0
	v_mov_b32_e32 v96, v0
	v_mov_b32_e32 v97, v0
	v_mov_b32_e32 v106, v0
	v_mov_b32_e32 v107, v0
	v_mov_b32_e32 v108, v0
	v_mov_b32_e32 v109, v0
	v_mov_b32_e32 v110, v0
	v_mov_b32_e32 v111, v0
	v_mov_b32_e32 v112, v0
	v_mov_b32_e32 v113, v0
	v_mov_b32_e32 v122, v0
	v_mov_b32_e32 v123, v0
	v_mov_b32_e32 v124, v0
	v_mov_b32_e32 v125, v0
	v_mov_b32_e32 v126, v0
	v_mov_b32_e32 v127, v0
	v_mov_b32_e32 v128, v0
	v_mov_b32_e32 v129, v0
	.p2align	6
